# s1 + gate/up epilogue conv-weight global load issued at tile start (v252 through the K loop), vmcnt(0) drain removed
# baseline (speedup 1.0000x reference)
.LBB0_982:
	s_lshl_b32 s100, s20, 7
	v_add_u32_e32 v250, s100, v171
	v_ashrrev_i32_e32 v251, 31, v250
	v_lshl_add_u64 v[250:251], v[250:251], 2, s[54:55]
	global_load_dword v252, v[250:251], off
	s_add_i32 s88, s88, 1
	v_readlane_b32 s2, v254, 57
	v_readlane_b32 s6, v254, 48
	s_mul_i32 s18, s88, s2
	s_mul_hi_u32 s19, s88, s6
	s_add_i32 s19, s19, s18
	s_mul_i32 s18, s88, s6
	v_readlane_b32 s2, v254, 47
	s_add_u32 s60, s18, s2
	s_addc_u32 s61, s19, 0
	v_mov_b64_e32 v[0:1], s[0:1]
	v_cmp_ge_i64_e32 vcc, s[60:61], v[0:1]
	v_cmp_lt_i64_e64 s[18:19], s[60:61], v[0:1]
	v_readlane_b32 s7, v254, 49
	s_cbranch_vccnz .LBB0_984
	s_ashr_i32 s21, s60, 31
	s_lshr_b32 s21, s21, 29
	s_add_i32 s21, s60, s21
	s_ashr_i32 s56, s21, 3
	s_and_b32 s21, s21, -8
	s_sub_i32 s21, s60, s21
	s_lshr_b32 s57, s21, 31
	s_or_b32 s57, s89, s57
	s_mul_i32 s21, s57, s21
	s_add_i32 s21, s21, s56
	s_mul_hi_i32 s56, s21, 0x2e8ba2e9
	s_lshr_b32 s57, s56, 31
	s_ashr_i32 s56, s56, 6
	s_add_i32 s56, s56, s57
	s_lshl_b32 s57, s56, 3
	s_sub_i32 s58, s68, s57
	s_min_i32 s58, s58, 8
	s_abs_i32 s59, s58
	v_cvt_f32_u32_e32 v0, s59
	s_sub_i32 s61, 0, s59
	s_mulk_i32 s56, 0x160
	s_sub_i32 s21, s21, s56
	v_rcp_iflag_f32_e32 v0, v0
	s_abs_i32 s56, s21
	s_xor_b32 s60, s21, s58
	s_ashr_i32 s60, s60, 31
	v_mul_f32_e32 v0, 0x4f7ffffe, v0
	v_cvt_u32_f32_e32 v0, v0
	s_nop 0
	v_readfirstlane_b32 s62, v0
	s_mul_i32 s61, s61, s62
	s_mul_hi_u32 s61, s62, s61
	s_add_i32 s62, s62, s61
	s_mul_hi_u32 s61, s56, s62
	s_mul_i32 s62, s61, s59
	s_sub_i32 s56, s56, s62
	s_add_i32 s63, s61, 1
	s_sub_i32 s62, s56, s59
	s_cmp_ge_u32 s56, s59
	s_cselect_b32 s61, s63, s61
	s_cselect_b32 s56, s62, s56
	s_add_i32 s62, s61, 1
	s_cmp_ge_u32 s56, s59
	s_cselect_b32 s56, s62, s61
	s_xor_b32 s56, s56, s60
	s_sub_i32 s56, s56, s60
	s_mul_i32 s58, s56, s58
	s_sub_i32 s21, s21, s58
	s_add_i32 s58, s21, s57

.LBB0_999:
	s_or_b64 exec, exec, s[22:23]
	s_lshl_b32 s22, s20, 7
	v_mov_b32_e32 v150, 0
	s_and_b64 vcc, exec, s[10:11]
	v_mov_b32_e32 v128, 0
	v_mov_b32_e32 v130, 0
	v_mov_b32_e32 v131, 0
	ds_write_b32 v173, v252
	s_waitcnt lgkmcnt(0)
	s_barrier
	v_mov_b32_e32 v192, 0xbfb8aa3b
	v_mov_b32_e32 v193, 0xbfb8aa3b
	v_mov_b32_e32 v194, 1.0
	v_mov_b32_e32 v195, 1.0
	v_lshl_add_u32 v181, s24, 8, v165
	v_or_b32_e32 v182, s22, v167
	v_ashrrev_i32_e32 v183, 31, v182
	v_lshlrev_b64 v[182:183], 1, v[182:183]
	s_movk_i32 s2, 0x2c00
	ds_read_b128 v[128:131], v174 offset:0
	ds_read_b128 v[132:135], v174 offset:512
	ds_read_b128 v[136:139], v174 offset:1024
	ds_read_b128 v[140:143], v174 offset:1536
	v_mov_b64_e32 v[200:201], 0
	v_mov_b64_e32 v[202:203], 0
	v_mov_b64_e32 v[204:205], 0
	v_mov_b64_e32 v[206:207], 0
	s_and_b64 vcc, exec, s[10:11]
	s_cbranch_vccz .Lepi_a0
	ds_read_b128 v[200:203], v178
